# same edits as v36 but scalar temporaries moved to the compiler's long-branch pair s98/s99 (no descriptor change)
# baseline (speedup 1.0000x reference)
.LBB0_1391:
	s_lshl_b32 s0, s34, 5
	v_add_u32_e32 v120, s0, v170
	v_mad_i64_i32 v[0:1], s[2:3], v120, s33, v[116:117]
	s_mov_b32 s98, 0x28000
	s_mov_b32 s99, 0
	v_lshl_add_u64 v[200:201], v[0:1], 0, s[98:99]
	global_load_dword v202, v[200:201], off
	global_load_dwordx4 v[92:95], v[0:1], off
	global_load_dwordx4 v[88:91], v[0:1], off offset:32
	global_load_dwordx4 v[84:87], v[0:1], off offset:64
	global_load_dwordx4 v[80:83], v[0:1], off offset:96
	v_or_b32_e32 v0, s0, v122
	s_movk_i32 s31, 0x90
	v_mad_u64_u32 v[8:9], s[2:3], v0, s31, v[100:101]
	v_mov_b32 v64, 0
	v_mov_b32 v65, 0
	v_mov_b32 v66, 0
	v_mov_b32 v67, 0
	v_mov_b32 v68, 0
	v_mov_b32 v69, 0
	v_mov_b32 v70, 0
	v_mov_b32 v71, 0
	v_mov_b32 v72, 0
	v_mov_b32 v73, 0
	v_mov_b32 v74, 0
	v_mov_b32 v75, 0
	v_mov_b32 v76, 0
	v_mov_b32 v77, 0
	v_mov_b32 v78, 0
	v_mov_b32 v79, 0
	ds_read_b128 v[0:3], v8
	ds_read_b128 v[4:7], v8 offset:32
	s_add_i32 s10, s34, 1
	s_lshl_b32 s30, s10, 5
	s_add_i32 s29, s34, 2
	s_lshl_b32 s7, s29, 5
	s_add_i32 s12, s34, 3
	s_add_i32 s13, s34, 4
	s_waitcnt vmcnt(3) lgkmcnt(1)
	v_mfma_f32_32x32x16_f16 v[64:79], v[0:3], v[92:95], v[64:79]
	ds_read_b128 v[0:3], v8 offset:64
	s_waitcnt vmcnt(2) lgkmcnt(1)
	v_mfma_f32_32x32x16_f16 v[64:79], v[4:7], v[88:91], v[64:79]
	s_waitcnt vmcnt(1) lgkmcnt(0)
	v_mfma_f32_32x32x16_f16 v[64:79], v[0:3], v[84:87], v[64:79]
	ds_read_b128 v[0:3], v8 offset:96
	v_mov_b32 v48, 0
	v_mov_b32 v49, 0
	v_mov_b32 v50, 0
	v_mov_b32 v51, 0
	v_mov_b32 v52, 0
	v_mov_b32 v53, 0
	v_mov_b32 v54, 0
	v_mov_b32 v55, 0
	v_mov_b32 v56, 0
	v_mov_b32 v57, 0
	v_mov_b32 v58, 0
	v_mov_b32 v59, 0
	v_mov_b32 v60, 0
	v_mov_b32 v61, 0
	v_mov_b32 v62, 0
	v_mov_b32 v63, 0
	s_waitcnt vmcnt(0) lgkmcnt(0)
	v_mfma_f32_32x32x16_f16 v[64:79], v[0:3], v[80:83], v[64:79]
	v_or_b32_e32 v0, s30, v122
	v_mad_u64_u32 v[8:9], s[2:3], v0, s31, v[100:101]
	ds_read_b128 v[0:3], v8
	ds_read_b128 v[4:7], v8 offset:32
	s_waitcnt lgkmcnt(1)
	v_mfma_f32_32x32x16_f16 v[48:63], v[0:3], v[92:95], v[48:63]
	ds_read_b128 v[0:3], v8 offset:64
	s_waitcnt lgkmcnt(1)
	v_mfma_f32_32x32x16_f16 v[48:63], v[4:7], v[88:91], v[48:63]
	s_waitcnt lgkmcnt(0)
	v_mfma_f32_32x32x16_f16 v[48:63], v[0:3], v[84:87], v[48:63]
	ds_read_b128 v[0:3], v8 offset:96
	v_mov_b32 v32, 0
	v_mov_b32 v33, 0
	v_mov_b32 v34, 0
	v_mov_b32 v35, 0
	v_mov_b32 v36, 0
	v_mov_b32 v37, 0
	v_mov_b32 v38, 0
	v_mov_b32 v39, 0
	v_mov_b32 v40, 0
	v_mov_b32 v41, 0
	v_mov_b32 v42, 0
	v_mov_b32 v43, 0
	v_mov_b32 v44, 0
	v_mov_b32 v45, 0
	v_mov_b32 v46, 0
	v_mov_b32 v47, 0
	s_waitcnt lgkmcnt(0)
	v_mfma_f32_32x32x16_f16 v[48:63], v[0:3], v[80:83], v[48:63]
	v_or_b32_e32 v0, s7, v122
	v_mad_u64_u32 v[8:9], s[2:3], v0, s31, v[100:101]
	ds_read_b128 v[0:3], v8
	ds_read_b128 v[4:7], v8 offset:32
	s_lshl_b32 s3, s12, 5
	s_lshl_b32 s2, s13, 5
	v_or_b32_e32 v121, s2, v122
	s_waitcnt lgkmcnt(1)
	v_mfma_f32_32x32x16_f16 v[32:47], v[0:3], v[92:95], v[32:47]
	ds_read_b128 v[0:3], v8 offset:64
	v_mad_u64_u32 v[180:181], s[8:9], v121, s31, v[100:101]
	s_waitcnt lgkmcnt(1)
	v_mfma_f32_32x32x16_f16 v[32:47], v[4:7], v[88:91], v[32:47]
	s_waitcnt lgkmcnt(0)
	v_mfma_f32_32x32x16_f16 v[32:47], v[0:3], v[84:87], v[32:47]
	ds_read_b128 v[0:3], v8 offset:96
	v_mov_b32 v16, 0
	v_mov_b32 v17, 0
	v_mov_b32 v18, 0
	v_mov_b32 v19, 0
	v_mov_b32 v20, 0
	v_mov_b32 v21, 0
	v_mov_b32 v22, 0
	v_mov_b32 v23, 0
	v_mov_b32 v24, 0
	v_mov_b32 v25, 0
	v_mov_b32 v26, 0
	v_mov_b32 v27, 0
	v_mov_b32 v28, 0
	v_mov_b32 v29, 0
	v_mov_b32 v30, 0
	v_mov_b32 v31, 0
	s_waitcnt lgkmcnt(0)
	v_mfma_f32_32x32x16_f16 v[32:47], v[0:3], v[80:83], v[32:47]
	v_or_b32_e32 v0, s3, v122
	v_mad_u64_u32 v[8:9], s[8:9], v0, s31, v[100:101]
	ds_read_b128 v[0:3], v8
	ds_read_b128 v[4:7], v8 offset:32
	s_waitcnt lgkmcnt(1)
	v_mfma_f32_32x32x16_f16 v[16:31], v[0:3], v[92:95], v[16:31]
	ds_read_b128 v[0:3], v8 offset:64
	s_waitcnt lgkmcnt(1)
	v_mfma_f32_32x32x16_f16 v[16:31], v[4:7], v[88:91], v[16:31]
	s_waitcnt lgkmcnt(0)
	v_mfma_f32_32x32x16_f16 v[16:31], v[0:3], v[84:87], v[16:31]
	ds_read_b128 v[0:3], v8 offset:96
	s_waitcnt lgkmcnt(0)
	v_mfma_f32_32x32x16_f16 v[16:31], v[0:3], v[80:83], v[16:31]
	v_mov_b32 v0, 0
	v_mov_b32 v1, 0
	v_mov_b32 v2, 0
	v_mov_b32 v3, 0
	v_mov_b32 v4, 0
	v_mov_b32 v5, 0
	v_mov_b32 v6, 0
	v_mov_b32 v7, 0
	v_mov_b32 v8, 0
	v_mov_b32 v9, 0
	v_mov_b32 v10, 0
	v_mov_b32 v11, 0
	v_mov_b32 v12, 0
	v_mov_b32 v13, 0
	v_mov_b32 v14, 0
	v_mov_b32 v15, 0
	ds_read_b128 v[172:175], v180
	ds_read_b128 v[176:179], v180 offset:32
	s_waitcnt lgkmcnt(1)
	v_mfma_f32_32x32x16_f16 v[0:15], v[172:175], v[92:95], v[0:15]
	s_waitcnt lgkmcnt(0)
	v_mfma_f32_32x32x16_f16 v[0:15], v[176:179], v[88:91], v[0:15]
	ds_read_b128 v[88:91], v180 offset:64
	s_waitcnt lgkmcnt(0)
	v_mfma_f32_32x32x16_f16 v[0:15], v[88:91], v[84:87], v[0:15]
	ds_read_b128 v[84:87], v180 offset:96
	s_waitcnt lgkmcnt(0)
	v_mfma_f32_32x32x16_f16 v[0:15], v[84:87], v[80:83], v[0:15]
	v_add_u32_e32 v85, s0, v102
	v_cmp_lt_i32_e32 vcc, s90, v85
	s_or_b64 s[8:9], s[22:23], vcc
	s_and_b64 s[36:37], s[40:41], s[8:9]
	v_mov_b32_e32 v80, 0xf149f2ca
	v_mov_b32_e32 v81, 0xf149f2ca
	s_and_saveexec_b64 s[8:9], s[36:37]
	s_cbranch_execz .LBB0_1393
	ds_read_b32 v81, v128 offset:512
	s_waitcnt lgkmcnt(0)
	v_add_f32_e32 v81, v64, v81

.LBB0_1800:
	s_or_b64 exec, exec, s[8:9]
	s_waitcnt lgkmcnt(0)
	s_barrier
	s_ashr_i32 s0, s18, 2
	s_lshl_b32 s2, s0, 10
	s_lshl_b32 s0, s0, 6
	v_and_b32_e32 v128, 15, v169
	s_add_i32 s0, s0, s42
	s_add_i32 s2, s2, 0
	v_or_b32_e32 v140, s0, v128
	s_lshl_b32 s0, s34, 2
	s_add_u32 s16, s10, s0
	s_addc_u32 s17, s27, 0
	v_ashrrev_i32_e32 v141, 31, v140
	s_lshl_b32 s3, s18, 6
	v_lshrrev_b32_e32 v134, 2, v169
	v_lshlrev_b64 v[132:133], 13, v[140:141]
	s_lshl_b32 s0, s34, 1
	s_and_b32 s3, s3, 0xc0
	v_or_b32_e32 v132, s0, v132
	v_and_or_b32 v134, v134, 12, s3
	v_lshl_add_u64 v[130:131], s[36:37], 0, v[132:133]
	v_lshlrev_b32_e32 v224, 1, v134
	v_lshl_add_u64 v[170:171], v[130:131], 0, v[224:225]
	s_mov_b32 s98, 0x20000
	s_mov_b32 s99, 0
	v_lshl_add_u64 v[196:197], v[170:171], 0, s[98:99]
	global_load_dword v198, v[196:197], off
	global_load_dword v198, v[196:197], off offset:512
	v_lshl_add_u64 v[196:197], v[196:197], 0, s[98:99]
	global_load_dword v198, v[196:197], off
	global_load_dword v198, v[196:197], off offset:512
	v_lshl_add_u64 v[196:197], v[196:197], 0, s[98:99]
	global_load_dword v198, v[196:197], off
	global_load_dword v198, v[196:197], off offset:512
	global_load_dwordx2 v[172:173], v[170:171], off
	v_lshlrev_b32_e32 v141, 2, v134
	global_load_dwordx4 v[148:151], v141, s[16:17]
	global_load_dwordx2 v[174:175], v[170:171], off offset:32
	global_load_dwordx4 v[152:155], v141, s[16:17] offset:64
	global_load_dwordx2 v[180:181], v[170:171], off offset:64
	v_mul_f32_e32 v142, 0x3b000000, v129
	v_lshl_add_u32 v146, v128, 4, s2
	v_pk_add_f32 v[176:177], v[124:125], v[142:143] op_sel_hi:[1,0] neg_lo:[0,1] neg_hi:[0,1]
	v_add_u32_e32 v124, 0x11000, v146
	v_add_u32_e32 v125, 0x11100, v146
	v_pk_add_f32 v[178:179], v[126:127], v[142:143] op_sel_hi:[1,0] neg_lo:[0,1] neg_hi:[0,1]
	ds_read_b128 v[128:131], v124
	ds_read_b128 v[124:127], v125
	global_load_dwordx4 v[156:159], v141, s[16:17] offset:128
	global_load_dwordx4 v[160:163], v141, s[16:17] offset:192
	global_load_dwordx4 v[164:167], v141, s[16:17] offset:1024
	global_load_dwordx4 v[136:139], v141, s[16:17] offset:1088
	global_load_dwordx2 v[184:185], v[170:171], off offset:96
	v_lshl_add_u64 v[182:183], s[40:41], 0, v[132:133]
	v_pk_add_f32 v[120:121], v[120:121], v[142:143] op_sel_hi:[1,0] neg_lo:[0,1] neg_hi:[0,1]
	s_waitcnt lgkmcnt(1)
	v_mov_b32_e32 v132, v129
	v_mov_b32_e32 v133, v130
	v_mov_b32_e32 v129, v131
	v_pk_add_f32 v[128:129], v[132:133], v[128:129]
	v_pk_add_f32 v[122:123], v[122:123], v[142:143] op_sel_hi:[1,0] neg_lo:[0,1] neg_hi:[0,1]
	v_add_f32_e32 v128, v128, v129
	v_fmamk_f32 v128, v128, 0x3b000000, v245
	v_mul_f32_e32 v129, 0x4f800000, v128
	v_cmp_gt_f32_e32 vcc, s87, v128
	v_pk_add_f32 v[116:117], v[116:117], v[142:143] op_sel_hi:[1,0] neg_lo:[0,1] neg_hi:[0,1]
	v_pk_add_f32 v[118:119], v[118:119], v[142:143] op_sel_hi:[1,0] neg_lo:[0,1] neg_hi:[0,1]
	v_cndmask_b32_e32 v147, v128, v129, vcc
	global_load_dwordx4 v[132:135], v141, s[16:17] offset:1152
	global_load_dwordx4 v[128:131], v141, s[16:17] offset:1216
	global_load_dwordx2 v[186:187], v[170:171], off offset:512
	v_sqrt_f32_e32 v168, v147
	v_pk_add_f32 v[108:109], v[108:109], v[142:143] op_sel_hi:[1,0] neg_lo:[0,1] neg_hi:[0,1]
	v_pk_add_f32 v[110:111], v[110:111], v[142:143] op_sel_hi:[1,0] neg_lo:[0,1] neg_hi:[0,1]
	v_pk_add_f32 v[104:105], v[104:105], v[142:143] op_sel_hi:[1,0] neg_lo:[0,1] neg_hi:[0,1]
	v_add_u32_e32 v188, -1, v168
	v_add_u32_e32 v189, 1, v168
	v_fma_f32 v190, -v188, v168, v147
	v_fma_f32 v191, -v189, v168, v147
	v_cmp_ge_f32_e64 s[38:39], 0, v190
	v_pk_add_f32 v[106:107], v[106:107], v[142:143] op_sel_hi:[1,0] neg_lo:[0,1] neg_hi:[0,1]
	v_pk_add_f32 v[100:101], v[100:101], v[142:143] op_sel_hi:[1,0] neg_lo:[0,1] neg_hi:[0,1]
	v_cndmask_b32_e64 v168, v168, v188, s[38:39]
	v_cmp_lt_f32_e64 s[38:39], 0, v191
	v_pk_add_f32 v[102:103], v[102:103], v[142:143] op_sel_hi:[1,0] neg_lo:[0,1] neg_hi:[0,1]
	v_pk_add_f32 v[96:97], v[96:97], v[142:143] op_sel_hi:[1,0] neg_lo:[0,1] neg_hi:[0,1]
	v_cndmask_b32_e64 v168, v168, v189, s[38:39]
	v_mul_f32_e32 v188, 0x37800000, v168
	v_cndmask_b32_e32 v168, v168, v188, vcc
	global_load_dwordx2 v[188:189], v[170:171], off offset:544
	global_load_dwordx2 v[190:191], v[170:171], off offset:576
	s_nop 0
	global_load_dwordx2 v[170:171], v[170:171], off offset:608
	v_cmp_class_f32_e32 vcc, v147, v243
	v_pk_add_f32 v[98:99], v[98:99], v[142:143] op_sel_hi:[1,0] neg_lo:[0,1] neg_hi:[0,1]
	s_add_i32 s29, s29, s94
	v_cndmask_b32_e32 v147, v168, v147, vcc
	v_div_scale_f32 v168, s[2:3], v147, v147, 1.0
	v_rcp_f32_e32 v192, v168
	v_div_scale_f32 v193, vcc, 1.0, v147, 1.0
	s_add_i32 s28, s28, s66
	v_fma_f32 v194, -v168, v192, 1.0
	v_fmac_f32_e32 v192, v194, v192
	v_mul_f32_e32 v194, v193, v192
	v_fma_f32 v195, -v168, v194, v193
	v_fmac_f32_e32 v194, v195, v192
	v_fma_f32 v168, -v168, v194, v193
	v_div_fmas_f32 v168, v168, v192, v194
	v_div_fixup_f32 v168, v168, v147, 1.0
	v_pk_mul_f32 v[176:177], v[176:177], v[168:169] op_sel_hi:[1,0]
	v_pk_mul_f32 v[178:179], v[178:179], v[168:169] op_sel_hi:[1,0]
	v_pk_mul_f32 v[120:121], v[120:121], v[168:169] op_sel_hi:[1,0]
	v_pk_mul_f32 v[122:123], v[122:123], v[168:169] op_sel_hi:[1,0]
	v_pk_mul_f32 v[116:117], v[116:117], v[168:169] op_sel_hi:[1,0]
	v_pk_mul_f32 v[118:119], v[118:119], v[168:169] op_sel_hi:[1,0]
	v_pk_mul_f32 v[108:109], v[108:109], v[168:169] op_sel_hi:[1,0]
	v_pk_mul_f32 v[110:111], v[110:111], v[168:169] op_sel_hi:[1,0]
	v_pk_mul_f32 v[104:105], v[104:105], v[168:169] op_sel_hi:[1,0]
	v_pk_mul_f32 v[106:107], v[106:107], v[168:169] op_sel_hi:[1,0]
	v_pk_mul_f32 v[100:101], v[100:101], v[168:169] op_sel_hi:[1,0]
	v_pk_mul_f32 v[102:103], v[102:103], v[168:169] op_sel_hi:[1,0]
	v_pk_mul_f32 v[96:97], v[96:97], v[168:169] op_sel_hi:[1,0]
	v_pk_mul_f32 v[98:99], v[98:99], v[168:169] op_sel_hi:[1,0]
	s_cmpk_lt_i32 s29, 0x400
	s_waitcnt vmcnt(15)
	v_cvt_f32_f16_e32 v192, v172
	v_cvt_f32_f16_sdwa v193, v172 dst_sel:DWORD dst_unused:UNUSED_PAD src0_sel:WORD_1
	v_cvt_f32_f16_e32 v172, v173
	v_cvt_f32_f16_sdwa v173, v173 dst_sel:DWORD dst_unused:UNUSED_PAD src0_sel:WORD_1
	s_waitcnt vmcnt(14)
	v_pk_mul_f32 v[148:149], v[148:149], v[176:177]
	v_pk_mul_f32 v[150:151], v[150:151], v[178:179]
	v_pk_mul_f32 v[148:149], v[148:149], v[192:193]
	v_pk_mul_f32 v[150:151], v[150:151], v[172:173]
	v_cvt_pk_bf16_f32 v148, v148, v149
	v_cvt_pk_bf16_f32 v149, v150, v151
	v_lshl_add_u64 v[150:151], v[182:183], 0, v[224:225]
	global_store_dwordx2 v[150:151], v[148:149], off
	s_waitcnt vmcnt(14)
	v_cvt_f32_f16_e32 v148, v174
	v_cvt_f32_f16_sdwa v149, v174 dst_sel:DWORD dst_unused:UNUSED_PAD src0_sel:WORD_1
	s_waitcnt vmcnt(13)
	v_pk_mul_f32 v[120:121], v[152:153], v[120:121]
	v_pk_mul_f32 v[122:123], v[154:155], v[122:123]
	s_waitcnt vmcnt(11)
	v_pk_mul_f32 v[116:117], v[116:117], v[156:157]
	v_pk_mul_f32 v[120:121], v[120:121], v[148:149]
	v_cvt_f32_f16_e32 v148, v175
	v_cvt_f32_f16_sdwa v149, v175 dst_sel:DWORD dst_unused:UNUSED_PAD src0_sel:WORD_1
	v_cvt_pk_bf16_f32 v120, v120, v121
	v_pk_mul_f32 v[118:119], v[118:119], v[158:159]
	s_waitcnt vmcnt(10)
	v_pk_mul_f32 v[108:109], v[108:109], v[160:161]
	v_pk_mul_f32 v[122:123], v[122:123], v[148:149]
	v_pk_mul_f32 v[110:111], v[110:111], v[162:163]
	v_cvt_pk_bf16_f32 v121, v122, v123
	global_store_dwordx2 v[150:151], v[120:121], off offset:32
	v_cvt_f32_f16_e32 v120, v180
	v_cvt_f32_f16_sdwa v121, v180 dst_sel:DWORD dst_unused:UNUSED_PAD src0_sel:WORD_1
	s_waitcnt vmcnt(9)
	v_pk_mul_f32 v[104:105], v[104:105], v[136:137]
	v_pk_mul_f32 v[106:107], v[106:107], v[138:139]
	s_waitcnt vmcnt(7)
	v_pk_mul_f32 v[100:101], v[100:101], v[132:133]
	v_pk_mul_f32 v[116:117], v[116:117], v[120:121]
	v_cvt_f32_f16_e32 v120, v181
	v_cvt_f32_f16_sdwa v121, v181 dst_sel:DWORD dst_unused:UNUSED_PAD src0_sel:WORD_1
	v_cvt_pk_bf16_f32 v116, v116, v117
	v_pk_mul_f32 v[102:103], v[102:103], v[134:135]
	s_waitcnt vmcnt(6)
	v_pk_mul_f32 v[96:97], v[96:97], v[128:129]
	v_pk_mul_f32 v[118:119], v[118:119], v[120:121]
	v_pk_mul_f32 v[98:99], v[98:99], v[130:131]
	v_cvt_pk_bf16_f32 v117, v118, v119
	global_store_dwordx2 v[150:151], v[116:117], off offset:64
	v_cvt_f32_f16_e32 v116, v184
	v_cvt_f32_f16_sdwa v117, v184 dst_sel:DWORD dst_unused:UNUSED_PAD src0_sel:WORD_1
	v_pk_mul_f32 v[108:109], v[108:109], v[116:117]
	v_cvt_f32_f16_e32 v116, v185
	v_cvt_f32_f16_sdwa v117, v185 dst_sel:DWORD dst_unused:UNUSED_PAD src0_sel:WORD_1
	v_cvt_pk_bf16_f32 v108, v108, v109
	v_pk_mul_f32 v[110:111], v[110:111], v[116:117]
	s_nop 0
	v_cvt_pk_bf16_f32 v109, v110, v111
	global_store_dwordx2 v[150:151], v[108:109], off offset:96
	s_waitcnt vmcnt(7)
	v_cvt_f32_f16_e32 v108, v186
	v_cvt_f32_f16_sdwa v109, v186 dst_sel:DWORD dst_unused:UNUSED_PAD src0_sel:WORD_1
	v_pk_add_f32 v[110:111], v[112:113], v[142:143] op_sel_hi:[1,0] neg_lo:[0,1] neg_hi:[0,1]
	v_pk_add_f32 v[112:113], v[114:115], v[142:143] op_sel_hi:[1,0] neg_lo:[0,1] neg_hi:[0,1]
	v_pk_mul_f32 v[110:111], v[110:111], v[168:169] op_sel_hi:[1,0]
	v_pk_mul_f32 v[112:113], v[112:113], v[168:169] op_sel_hi:[1,0]
	v_pk_mul_f32 v[110:111], v[110:111], v[164:165]
	v_pk_mul_f32 v[112:113], v[112:113], v[166:167]
	v_pk_mul_f32 v[108:109], v[110:111], v[108:109]
	v_cvt_f32_f16_e32 v110, v187
	v_cvt_f32_f16_sdwa v111, v187 dst_sel:DWORD dst_unused:UNUSED_PAD src0_sel:WORD_1
	v_cvt_pk_bf16_f32 v108, v108, v109
	v_pk_mul_f32 v[110:111], v[112:113], v[110:111]
	s_nop 0
	v_cvt_pk_bf16_f32 v109, v110, v111
	global_store_dwordx2 v[150:151], v[108:109], off offset:512
	s_waitcnt vmcnt(7)
	v_cvt_f32_f16_e32 v108, v188
	v_cvt_f32_f16_sdwa v109, v188 dst_sel:DWORD dst_unused:UNUSED_PAD src0_sel:WORD_1
	v_pk_mul_f32 v[104:105], v[104:105], v[108:109]
	v_cvt_f32_f16_e32 v108, v189
	v_cvt_f32_f16_sdwa v109, v189 dst_sel:DWORD dst_unused:UNUSED_PAD src0_sel:WORD_1
	v_cvt_pk_bf16_f32 v104, v104, v105
	v_pk_mul_f32 v[106:107], v[106:107], v[108:109]
	s_nop 0
	v_cvt_pk_bf16_f32 v105, v106, v107
	global_store_dwordx2 v[150:151], v[104:105], off offset:544
	s_waitcnt vmcnt(7)
	v_cvt_f32_f16_e32 v104, v190
	v_cvt_f32_f16_sdwa v105, v190 dst_sel:DWORD dst_unused:UNUSED_PAD src0_sel:WORD_1
	v_pk_mul_f32 v[100:101], v[100:101], v[104:105]
	v_cvt_f32_f16_e32 v104, v191
	v_cvt_f32_f16_sdwa v105, v191 dst_sel:DWORD dst_unused:UNUSED_PAD src0_sel:WORD_1
	v_cvt_pk_bf16_f32 v100, v100, v101
	v_pk_mul_f32 v[102:103], v[102:103], v[104:105]
	s_nop 0
	v_cvt_pk_bf16_f32 v101, v102, v103
	global_store_dwordx2 v[150:151], v[100:101], off offset:576
	s_waitcnt vmcnt(7)
	v_cvt_f32_f16_e32 v100, v170
	v_cvt_f32_f16_sdwa v101, v170 dst_sel:DWORD dst_unused:UNUSED_PAD src0_sel:WORD_1
	v_pk_mul_f32 v[96:97], v[96:97], v[100:101]
	v_cvt_f32_f16_e32 v100, v171
	v_cvt_f32_f16_sdwa v101, v171 dst_sel:DWORD dst_unused:UNUSED_PAD src0_sel:WORD_1
	v_cvt_pk_bf16_f32 v96, v96, v97
	v_pk_mul_f32 v[98:99], v[98:99], v[100:101]
	s_nop 0
	v_cvt_pk_bf16_f32 v97, v98, v99
	global_store_dwordx2 v[150:151], v[96:97], off offset:608
	v_or_b32_e32 v96, 16, v140
	v_ashrrev_i32_e32 v97, 31, v96
	v_lshlrev_b64 v[132:133], 13, v[96:97]
	v_or_b32_e32 v132, s0, v132
	v_lshl_add_u64 v[96:97], s[36:37], 0, v[132:133]
	v_lshl_add_u64 v[134:135], v[96:97], 0, v[224:225]
	global_load_dwordx2 v[136:137], v[134:135], off
	global_load_dwordx4 v[100:103], v141, s[16:17]
	global_load_dwordx2 v[138:139], v[134:135], off offset:32
	global_load_dwordx4 v[104:107], v141, s[16:17] offset:64
	s_waitcnt lgkmcnt(0)
	v_mov_b32_e32 v96, v125
	v_mov_b32_e32 v97, v126
	v_mov_b32_e32 v125, v127
	v_pk_add_f32 v[96:97], v[96:97], v[124:125]
	global_load_dwordx2 v[148:149], v[134:135], off offset:64
	global_load_dwordx2 v[150:151], v[134:135], off offset:96
	global_load_dwordx2 v[152:153], v[134:135], off offset:512
	v_add_f32_e32 v96, v96, v97
	v_fmamk_f32 v96, v96, 0x3b000000, v245
	v_mul_f32_e32 v97, 0x4f800000, v96
	v_cmp_gt_f32_e32 vcc, s87, v96
	global_load_dwordx4 v[108:111], v141, s[16:17] offset:128
	global_load_dwordx4 v[112:115], v141, s[16:17] offset:192
	v_cndmask_b32_e32 v96, v96, v97, vcc
	v_sqrt_f32_e32 v97, v96
	v_lshl_add_u64 v[132:133], s[40:41], 0, v[132:133]
	v_add_u32_e32 v98, -1, v97
	v_fma_f32 v99, -v98, v97, v96
	v_cmp_ge_f32_e64 s[38:39], 0, v99
	v_add_u32_e32 v99, 1, v97
	s_waitcnt vmcnt(8)
	v_cvt_f32_f16_e32 v158, v136
	v_cndmask_b32_e64 v98, v97, v98, s[38:39]
	v_fma_f32 v97, -v99, v97, v96
	v_cmp_lt_f32_e64 s[38:39], 0, v97
	v_cvt_f32_f16_sdwa v159, v136 dst_sel:DWORD dst_unused:UNUSED_PAD src0_sel:WORD_1
	s_nop 0
	v_cndmask_b32_e64 v97, v98, v99, s[38:39]
	v_mul_f32_e32 v98, 0x37800000, v97
	v_cndmask_b32_e32 v97, v97, v98, vcc
	v_cmp_class_f32_e32 vcc, v96, v243
	s_nop 1
	v_cndmask_b32_e32 v97, v97, v96, vcc
	v_div_scale_f32 v98, s[2:3], v97, v97, 1.0
	v_rcp_f32_e32 v99, v98
	v_div_scale_f32 v120, vcc, 1.0, v97, 1.0
	v_mul_f32_e32 v96, 0x3b000000, v145
	v_fma_f32 v116, -v98, v99, 1.0
	v_fmac_f32_e32 v99, v116, v99
	global_load_dwordx4 v[116:119], v141, s[16:17] offset:1024
	v_mul_f32_e32 v121, v120, v99
	v_fma_f32 v122, -v98, v121, v120
	v_fmac_f32_e32 v121, v122, v99
	v_fma_f32 v98, -v98, v121, v120
	v_div_fmas_f32 v98, v98, v99, v121
	global_load_dwordx4 v[120:123], v141, s[16:17] offset:1088
	global_load_dwordx4 v[124:127], v141, s[16:17] offset:1152
	global_load_dwordx4 v[128:131], v141, s[16:17] offset:1216
	global_load_dwordx2 v[154:155], v[134:135], off offset:544
	global_load_dwordx2 v[156:157], v[134:135], off offset:576
	s_nop 0
	global_load_dwordx2 v[134:135], v[134:135], off offset:608
	v_div_fixup_f32 v98, v98, v97, 1.0
	v_pk_add_f32 v[40:41], v[40:41], v[96:97] op_sel_hi:[1,0] neg_lo:[0,1] neg_hi:[0,1]
	v_pk_add_f32 v[42:43], v[42:43], v[96:97] op_sel_hi:[1,0] neg_lo:[0,1] neg_hi:[0,1]
	v_pk_mul_f32 v[40:41], v[40:41], v[98:99] op_sel_hi:[1,0]
	v_pk_mul_f32 v[42:43], v[42:43], v[98:99] op_sel_hi:[1,0]
	s_waitcnt vmcnt(14)
	v_pk_mul_f32 v[40:41], v[40:41], v[100:101]
	v_cvt_f32_f16_e32 v100, v137
	v_cvt_f32_f16_sdwa v101, v137 dst_sel:DWORD dst_unused:UNUSED_PAD src0_sel:WORD_1
	v_pk_mul_f32 v[42:43], v[42:43], v[102:103]
	v_pk_mul_f32 v[40:41], v[40:41], v[158:159]
	v_pk_add_f32 v[36:37], v[36:37], v[96:97] op_sel_hi:[1,0] neg_lo:[0,1] neg_hi:[0,1]
	v_pk_mul_f32 v[42:43], v[42:43], v[100:101]
	v_cvt_pk_bf16_f32 v40, v40, v41
	v_cvt_pk_bf16_f32 v41, v42, v43
	v_lshl_add_u64 v[42:43], v[132:133], 0, v[224:225]
	global_store_dwordx2 v[42:43], v[40:41], off
	s_waitcnt vmcnt(14)
	v_cvt_f32_f16_e32 v40, v138
	v_cvt_f32_f16_sdwa v41, v138 dst_sel:DWORD dst_unused:UNUSED_PAD src0_sel:WORD_1
	v_pk_mul_f32 v[36:37], v[36:37], v[98:99] op_sel_hi:[1,0]
	v_pk_add_f32 v[38:39], v[38:39], v[96:97] op_sel_hi:[1,0] neg_lo:[0,1] neg_hi:[0,1]
	s_waitcnt vmcnt(13)
	v_pk_mul_f32 v[36:37], v[36:37], v[104:105]
	v_pk_mul_f32 v[38:39], v[38:39], v[98:99] op_sel_hi:[1,0]
	v_pk_mul_f32 v[36:37], v[36:37], v[40:41]
	v_cvt_f32_f16_e32 v40, v139
	v_cvt_f32_f16_sdwa v41, v139 dst_sel:DWORD dst_unused:UNUSED_PAD src0_sel:WORD_1
	v_pk_mul_f32 v[38:39], v[38:39], v[106:107]
	v_cvt_pk_bf16_f32 v36, v36, v37
	v_pk_add_f32 v[32:33], v[32:33], v[96:97] op_sel_hi:[1,0] neg_lo:[0,1] neg_hi:[0,1]
	v_pk_mul_f32 v[38:39], v[38:39], v[40:41]
	v_pk_mul_f32 v[32:33], v[32:33], v[98:99] op_sel_hi:[1,0]
	v_cvt_pk_bf16_f32 v37, v38, v39
	global_store_dwordx2 v[42:43], v[36:37], off offset:32
	s_waitcnt vmcnt(13)
	v_cvt_f32_f16_e32 v36, v148
	v_cvt_f32_f16_sdwa v37, v148 dst_sel:DWORD dst_unused:UNUSED_PAD src0_sel:WORD_1
	s_waitcnt vmcnt(10)
	v_pk_mul_f32 v[32:33], v[32:33], v[108:109]
	v_pk_add_f32 v[34:35], v[34:35], v[96:97] op_sel_hi:[1,0] neg_lo:[0,1] neg_hi:[0,1]
	v_pk_mul_f32 v[32:33], v[32:33], v[36:37]
	v_cvt_f32_f16_e32 v36, v149
	v_cvt_f32_f16_sdwa v37, v149 dst_sel:DWORD dst_unused:UNUSED_PAD src0_sel:WORD_1
	v_pk_mul_f32 v[34:35], v[34:35], v[98:99] op_sel_hi:[1,0]
	v_cvt_pk_bf16_f32 v32, v32, v33
	v_pk_mul_f32 v[34:35], v[34:35], v[110:111]
	s_nop 0
	v_pk_mul_f32 v[34:35], v[34:35], v[36:37]
	v_pk_add_f32 v[36:37], v[46:47], v[96:97] op_sel_hi:[1,0] neg_lo:[0,1] neg_hi:[0,1]
	v_cvt_pk_bf16_f32 v33, v34, v35
	global_store_dwordx2 v[42:43], v[32:33], off offset:64
	v_cvt_f32_f16_e32 v32, v150
	v_cvt_f32_f16_sdwa v33, v150 dst_sel:DWORD dst_unused:UNUSED_PAD src0_sel:WORD_1
	v_pk_add_f32 v[34:35], v[44:45], v[96:97] op_sel_hi:[1,0] neg_lo:[0,1] neg_hi:[0,1]
	v_pk_mul_f32 v[36:37], v[36:37], v[98:99] op_sel_hi:[1,0]
	v_pk_mul_f32 v[34:35], v[34:35], v[98:99] op_sel_hi:[1,0]
	s_waitcnt vmcnt(10)
	v_pk_mul_f32 v[36:37], v[36:37], v[114:115]
	v_pk_mul_f32 v[34:35], v[34:35], v[112:113]
	s_nop 0
	v_pk_mul_f32 v[32:33], v[34:35], v[32:33]
	v_cvt_f32_f16_e32 v34, v151
	v_cvt_f32_f16_sdwa v35, v151 dst_sel:DWORD dst_unused:UNUSED_PAD src0_sel:WORD_1
	v_cvt_pk_bf16_f32 v32, v32, v33
	v_pk_mul_f32 v[34:35], v[36:37], v[34:35]
	s_nop 0
	v_cvt_pk_bf16_f32 v33, v34, v35
	global_store_dwordx2 v[42:43], v[32:33], off offset:96
	v_cvt_f32_f16_e32 v32, v152
	v_cvt_f32_f16_sdwa v33, v152 dst_sel:DWORD dst_unused:UNUSED_PAD src0_sel:WORD_1
	v_pk_add_f32 v[34:35], v[92:93], v[96:97] op_sel_hi:[1,0] neg_lo:[0,1] neg_hi:[0,1]
	v_pk_add_f32 v[36:37], v[94:95], v[96:97] op_sel_hi:[1,0] neg_lo:[0,1] neg_hi:[0,1]
	v_pk_mul_f32 v[34:35], v[34:35], v[98:99] op_sel_hi:[1,0]
	v_pk_mul_f32 v[36:37], v[36:37], v[98:99] op_sel_hi:[1,0]
	s_waitcnt vmcnt(10)
	v_pk_mul_f32 v[34:35], v[34:35], v[116:117]
	s_nop 0
	v_pk_mul_f32 v[32:33], v[34:35], v[32:33]
	v_cvt_f32_f16_e32 v34, v153
	v_cvt_f32_f16_sdwa v35, v153 dst_sel:DWORD dst_unused:UNUSED_PAD src0_sel:WORD_1
	v_pk_mul_f32 v[36:37], v[36:37], v[118:119]
	v_cvt_pk_bf16_f32 v32, v32, v33
	v_pk_mul_f32 v[34:35], v[36:37], v[34:35]
	s_nop 0
	v_cvt_pk_bf16_f32 v33, v34, v35
	global_store_dwordx2 v[42:43], v[32:33], off offset:512
	s_waitcnt vmcnt(7)
	v_cvt_f32_f16_e32 v32, v154
	v_cvt_f32_f16_sdwa v33, v154 dst_sel:DWORD dst_unused:UNUSED_PAD src0_sel:WORD_1
	v_pk_add_f32 v[34:35], v[88:89], v[96:97] op_sel_hi:[1,0] neg_lo:[0,1] neg_hi:[0,1]
	v_pk_add_f32 v[36:37], v[90:91], v[96:97] op_sel_hi:[1,0] neg_lo:[0,1] neg_hi:[0,1]
	v_pk_mul_f32 v[34:35], v[34:35], v[98:99] op_sel_hi:[1,0]
	v_pk_mul_f32 v[36:37], v[36:37], v[98:99] op_sel_hi:[1,0]
	v_pk_mul_f32 v[34:35], v[34:35], v[120:121]
	v_pk_mul_f32 v[36:37], v[36:37], v[122:123]
	v_pk_mul_f32 v[32:33], v[34:35], v[32:33]
	v_cvt_f32_f16_e32 v34, v155
	v_cvt_f32_f16_sdwa v35, v155 dst_sel:DWORD dst_unused:UNUSED_PAD src0_sel:WORD_1
	v_cvt_pk_bf16_f32 v32, v32, v33
	v_pk_mul_f32 v[34:35], v[36:37], v[34:35]
	s_nop 0
	v_cvt_pk_bf16_f32 v33, v34, v35
	global_store_dwordx2 v[42:43], v[32:33], off offset:544
	s_waitcnt vmcnt(7)
	v_cvt_f32_f16_e32 v32, v156
	v_cvt_f32_f16_sdwa v33, v156 dst_sel:DWORD dst_unused:UNUSED_PAD src0_sel:WORD_1
	v_pk_add_f32 v[34:35], v[84:85], v[96:97] op_sel_hi:[1,0] neg_lo:[0,1] neg_hi:[0,1]
	v_pk_add_f32 v[36:37], v[86:87], v[96:97] op_sel_hi:[1,0] neg_lo:[0,1] neg_hi:[0,1]
	v_pk_mul_f32 v[34:35], v[34:35], v[98:99] op_sel_hi:[1,0]
	v_pk_mul_f32 v[36:37], v[36:37], v[98:99] op_sel_hi:[1,0]
	v_pk_mul_f32 v[34:35], v[34:35], v[124:125]
	v_pk_mul_f32 v[36:37], v[36:37], v[126:127]
	v_pk_mul_f32 v[32:33], v[34:35], v[32:33]
	v_cvt_f32_f16_e32 v34, v157
	v_cvt_f32_f16_sdwa v35, v157 dst_sel:DWORD dst_unused:UNUSED_PAD src0_sel:WORD_1
	v_cvt_pk_bf16_f32 v32, v32, v33
	v_pk_mul_f32 v[34:35], v[36:37], v[34:35]
	s_nop 0
	v_cvt_pk_bf16_f32 v33, v34, v35
	global_store_dwordx2 v[42:43], v[32:33], off offset:576
	s_waitcnt vmcnt(7)
	v_cvt_f32_f16_e32 v32, v134
	v_cvt_f32_f16_sdwa v33, v134 dst_sel:DWORD dst_unused:UNUSED_PAD src0_sel:WORD_1
	v_pk_add_f32 v[34:35], v[80:81], v[96:97] op_sel_hi:[1,0] neg_lo:[0,1] neg_hi:[0,1]
	v_pk_add_f32 v[36:37], v[82:83], v[96:97] op_sel_hi:[1,0] neg_lo:[0,1] neg_hi:[0,1]
	v_pk_mul_f32 v[34:35], v[34:35], v[98:99] op_sel_hi:[1,0]
	v_pk_mul_f32 v[36:37], v[36:37], v[98:99] op_sel_hi:[1,0]
	v_pk_mul_f32 v[34:35], v[34:35], v[128:129]
	v_pk_mul_f32 v[36:37], v[36:37], v[130:131]
	v_pk_mul_f32 v[32:33], v[34:35], v[32:33]
	v_cvt_f32_f16_e32 v34, v135
	v_cvt_f32_f16_sdwa v35, v135 dst_sel:DWORD dst_unused:UNUSED_PAD src0_sel:WORD_1
	v_cvt_pk_bf16_f32 v32, v32, v33
	v_pk_mul_f32 v[34:35], v[36:37], v[34:35]
	s_nop 0
	v_cvt_pk_bf16_f32 v33, v34, v35
	global_store_dwordx2 v[42:43], v[32:33], off offset:608
	v_or_b32_e32 v32, 32, v140
	v_ashrrev_i32_e32 v33, 31, v32
	v_lshlrev_b64 v[104:105], 13, v[32:33]
	v_or_b32_e32 v104, s0, v104
	v_lshl_add_u64 v[32:33], s[36:37], 0, v[104:105]
	v_lshl_add_u64 v[106:107], v[32:33], 0, v[224:225]
	global_load_dwordx2 v[108:109], v[106:107], off
	global_load_dwordx4 v[40:43], v141, s[16:17]
	global_load_dwordx2 v[110:111], v[106:107], off offset:32
	v_add_u32_e32 v32, 0x11200, v146
	ds_read_b128 v[36:39], v32
	global_load_dwordx4 v[44:47], v141, s[16:17] offset:64
	global_load_dwordx2 v[112:113], v[106:107], off offset:64
	global_load_dwordx2 v[114:115], v[106:107], off offset:96
	global_load_dwordx2 v[116:117], v[106:107], off offset:512
	s_waitcnt lgkmcnt(0)
	v_mov_b32_e32 v80, v37
	v_mov_b32_e32 v81, v38
	v_mov_b32_e32 v37, v39
	v_pk_add_f32 v[36:37], v[80:81], v[36:37]
	global_load_dwordx4 v[80:83], v141, s[16:17] offset:128
	v_add_f32_e32 v36, v36, v37
	v_fmamk_f32 v36, v36, 0x3b000000, v245
	v_mul_f32_e32 v37, 0x4f800000, v36
	v_cmp_gt_f32_e32 vcc, s87, v36
	global_load_dwordx4 v[84:87], v141, s[16:17] offset:192
	v_add_u32_e32 v32, 0x11300, v146
	v_cndmask_b32_e32 v36, v36, v37, vcc
	v_sqrt_f32_e32 v37, v36
	ds_read_b128 v[32:35], v32
	v_lshl_add_u64 v[104:105], s[40:41], 0, v[104:105]
	v_add_u32_e32 v38, -1, v37
	v_fma_f32 v39, -v38, v37, v36
	v_cmp_ge_f32_e64 s[38:39], 0, v39
	v_add_u32_e32 v39, 1, v37
	s_waitcnt vmcnt(8)
	v_cvt_f32_f16_e32 v122, v108
	v_cndmask_b32_e64 v38, v37, v38, s[38:39]
	v_fma_f32 v37, -v39, v37, v36
	v_cmp_lt_f32_e64 s[38:39], 0, v37
	v_cvt_f32_f16_sdwa v123, v108 dst_sel:DWORD dst_unused:UNUSED_PAD src0_sel:WORD_1
	s_nop 0
	v_cndmask_b32_e64 v37, v38, v39, s[38:39]
	v_mul_f32_e32 v38, 0x37800000, v37
	v_cndmask_b32_e32 v37, v37, v38, vcc
	v_cmp_class_f32_e32 vcc, v36, v243
	s_nop 1
	v_cndmask_b32_e32 v37, v37, v36, vcc
	v_div_scale_f32 v38, s[2:3], v37, v37, 1.0
	v_rcp_f32_e32 v39, v38
	v_div_scale_f32 v92, vcc, 1.0, v37, 1.0
	v_mul_f32_e32 v36, 0x3b000000, v144
	v_fma_f32 v88, -v38, v39, 1.0
	v_fmac_f32_e32 v39, v88, v39
	global_load_dwordx4 v[88:91], v141, s[16:17] offset:1024
	v_mul_f32_e32 v93, v92, v39
	v_fma_f32 v94, -v38, v93, v92
	v_fmac_f32_e32 v93, v94, v39
	v_fma_f32 v38, -v38, v93, v92
	v_div_fmas_f32 v38, v38, v39, v93
	global_load_dwordx4 v[92:95], v141, s[16:17] offset:1088
	global_load_dwordx4 v[96:99], v141, s[16:17] offset:1152
	global_load_dwordx4 v[100:103], v141, s[16:17] offset:1216
	global_load_dwordx2 v[118:119], v[106:107], off offset:544
	global_load_dwordx2 v[120:121], v[106:107], off offset:576
	s_nop 0
	global_load_dwordx2 v[106:107], v[106:107], off offset:608
	v_div_fixup_f32 v38, v38, v37, 1.0
	v_pk_add_f32 v[24:25], v[24:25], v[36:37] op_sel_hi:[1,0] neg_lo:[0,1] neg_hi:[0,1]
	v_pk_add_f32 v[26:27], v[26:27], v[36:37] op_sel_hi:[1,0] neg_lo:[0,1] neg_hi:[0,1]
	v_pk_mul_f32 v[24:25], v[24:25], v[38:39] op_sel_hi:[1,0]
	v_pk_mul_f32 v[26:27], v[26:27], v[38:39] op_sel_hi:[1,0]
	s_waitcnt vmcnt(14)
	v_pk_mul_f32 v[24:25], v[24:25], v[40:41]
	v_cvt_f32_f16_e32 v40, v109
	v_cvt_f32_f16_sdwa v41, v109 dst_sel:DWORD dst_unused:UNUSED_PAD src0_sel:WORD_1
	v_pk_mul_f32 v[26:27], v[26:27], v[42:43]
	v_pk_mul_f32 v[24:25], v[24:25], v[122:123]
	v_pk_add_f32 v[20:21], v[20:21], v[36:37] op_sel_hi:[1,0] neg_lo:[0,1] neg_hi:[0,1]
	v_pk_mul_f32 v[26:27], v[26:27], v[40:41]
	v_cvt_pk_bf16_f32 v24, v24, v25
	v_cvt_pk_bf16_f32 v25, v26, v27
	v_lshl_add_u64 v[26:27], v[104:105], 0, v[224:225]
	global_store_dwordx2 v[26:27], v[24:25], off
	s_waitcnt vmcnt(14)
	v_cvt_f32_f16_e32 v24, v110
	v_cvt_f32_f16_sdwa v25, v110 dst_sel:DWORD dst_unused:UNUSED_PAD src0_sel:WORD_1
	v_pk_mul_f32 v[20:21], v[20:21], v[38:39] op_sel_hi:[1,0]
	v_pk_add_f32 v[22:23], v[22:23], v[36:37] op_sel_hi:[1,0] neg_lo:[0,1] neg_hi:[0,1]
	s_waitcnt vmcnt(13)
	v_pk_mul_f32 v[20:21], v[20:21], v[44:45]
	v_pk_mul_f32 v[22:23], v[22:23], v[38:39] op_sel_hi:[1,0]
	v_pk_mul_f32 v[20:21], v[20:21], v[24:25]
	v_cvt_f32_f16_e32 v24, v111
	v_cvt_f32_f16_sdwa v25, v111 dst_sel:DWORD dst_unused:UNUSED_PAD src0_sel:WORD_1
	v_pk_mul_f32 v[22:23], v[22:23], v[46:47]
	v_cvt_pk_bf16_f32 v20, v20, v21
	v_pk_add_f32 v[16:17], v[16:17], v[36:37] op_sel_hi:[1,0] neg_lo:[0,1] neg_hi:[0,1]
	v_pk_mul_f32 v[22:23], v[22:23], v[24:25]
	v_pk_mul_f32 v[16:17], v[16:17], v[38:39] op_sel_hi:[1,0]
	v_cvt_pk_bf16_f32 v21, v22, v23
	global_store_dwordx2 v[26:27], v[20:21], off offset:32
	s_waitcnt vmcnt(13)
	v_cvt_f32_f16_e32 v20, v112
	v_cvt_f32_f16_sdwa v21, v112 dst_sel:DWORD dst_unused:UNUSED_PAD src0_sel:WORD_1
	s_waitcnt vmcnt(10)
	v_pk_mul_f32 v[16:17], v[16:17], v[80:81]
	v_pk_add_f32 v[18:19], v[18:19], v[36:37] op_sel_hi:[1,0] neg_lo:[0,1] neg_hi:[0,1]
	v_pk_mul_f32 v[16:17], v[16:17], v[20:21]
	v_cvt_f32_f16_e32 v20, v113
	v_cvt_f32_f16_sdwa v21, v113 dst_sel:DWORD dst_unused:UNUSED_PAD src0_sel:WORD_1
	v_pk_mul_f32 v[18:19], v[18:19], v[38:39] op_sel_hi:[1,0]
	v_cvt_pk_bf16_f32 v16, v16, v17
	v_pk_mul_f32 v[18:19], v[18:19], v[82:83]
	s_nop 0
	v_pk_mul_f32 v[18:19], v[18:19], v[20:21]
	v_pk_add_f32 v[20:21], v[30:31], v[36:37] op_sel_hi:[1,0] neg_lo:[0,1] neg_hi:[0,1]
	v_cvt_pk_bf16_f32 v17, v18, v19
	global_store_dwordx2 v[26:27], v[16:17], off offset:64
	v_cvt_f32_f16_e32 v16, v114
	v_cvt_f32_f16_sdwa v17, v114 dst_sel:DWORD dst_unused:UNUSED_PAD src0_sel:WORD_1
	v_pk_add_f32 v[18:19], v[28:29], v[36:37] op_sel_hi:[1,0] neg_lo:[0,1] neg_hi:[0,1]
	v_pk_mul_f32 v[20:21], v[20:21], v[38:39] op_sel_hi:[1,0]
	v_pk_mul_f32 v[18:19], v[18:19], v[38:39] op_sel_hi:[1,0]
	s_waitcnt vmcnt(10)
	v_pk_mul_f32 v[20:21], v[20:21], v[86:87]
	v_pk_mul_f32 v[18:19], v[18:19], v[84:85]
	s_nop 0
	v_pk_mul_f32 v[16:17], v[18:19], v[16:17]
	v_cvt_f32_f16_e32 v18, v115
	v_cvt_f32_f16_sdwa v19, v115 dst_sel:DWORD dst_unused:UNUSED_PAD src0_sel:WORD_1
	v_cvt_pk_bf16_f32 v16, v16, v17
	v_pk_mul_f32 v[18:19], v[20:21], v[18:19]
	s_nop 0
	v_cvt_pk_bf16_f32 v17, v18, v19
	global_store_dwordx2 v[26:27], v[16:17], off offset:96
	v_cvt_f32_f16_e32 v16, v116
	v_cvt_f32_f16_sdwa v17, v116 dst_sel:DWORD dst_unused:UNUSED_PAD src0_sel:WORD_1
	v_pk_add_f32 v[18:19], v[76:77], v[36:37] op_sel_hi:[1,0] neg_lo:[0,1] neg_hi:[0,1]
	v_pk_add_f32 v[20:21], v[78:79], v[36:37] op_sel_hi:[1,0] neg_lo:[0,1] neg_hi:[0,1]
	v_pk_mul_f32 v[18:19], v[18:19], v[38:39] op_sel_hi:[1,0]
	v_pk_mul_f32 v[20:21], v[20:21], v[38:39] op_sel_hi:[1,0]
	s_waitcnt vmcnt(10)
	v_pk_mul_f32 v[18:19], v[18:19], v[88:89]
	s_nop 0
	v_pk_mul_f32 v[16:17], v[18:19], v[16:17]
	v_cvt_f32_f16_e32 v18, v117
	v_cvt_f32_f16_sdwa v19, v117 dst_sel:DWORD dst_unused:UNUSED_PAD src0_sel:WORD_1
	v_pk_mul_f32 v[20:21], v[20:21], v[90:91]
	v_cvt_pk_bf16_f32 v16, v16, v17
	v_pk_mul_f32 v[18:19], v[20:21], v[18:19]
	s_nop 0
	v_cvt_pk_bf16_f32 v17, v18, v19
	global_store_dwordx2 v[26:27], v[16:17], off offset:512
	s_waitcnt vmcnt(7)
	v_cvt_f32_f16_e32 v16, v118
	v_cvt_f32_f16_sdwa v17, v118 dst_sel:DWORD dst_unused:UNUSED_PAD src0_sel:WORD_1
	v_pk_add_f32 v[18:19], v[72:73], v[36:37] op_sel_hi:[1,0] neg_lo:[0,1] neg_hi:[0,1]
	v_pk_add_f32 v[20:21], v[74:75], v[36:37] op_sel_hi:[1,0] neg_lo:[0,1] neg_hi:[0,1]
	v_pk_mul_f32 v[18:19], v[18:19], v[38:39] op_sel_hi:[1,0]
	v_pk_mul_f32 v[20:21], v[20:21], v[38:39] op_sel_hi:[1,0]
	v_pk_mul_f32 v[18:19], v[18:19], v[92:93]
	v_pk_mul_f32 v[20:21], v[20:21], v[94:95]
	v_pk_mul_f32 v[16:17], v[18:19], v[16:17]
	v_cvt_f32_f16_e32 v18, v119
	v_cvt_f32_f16_sdwa v19, v119 dst_sel:DWORD dst_unused:UNUSED_PAD src0_sel:WORD_1
	v_cvt_pk_bf16_f32 v16, v16, v17
	v_pk_mul_f32 v[18:19], v[20:21], v[18:19]
	s_nop 0
	v_cvt_pk_bf16_f32 v17, v18, v19
	global_store_dwordx2 v[26:27], v[16:17], off offset:544
	s_waitcnt vmcnt(7)
	v_cvt_f32_f16_e32 v16, v120
	v_cvt_f32_f16_sdwa v17, v120 dst_sel:DWORD dst_unused:UNUSED_PAD src0_sel:WORD_1
	v_pk_add_f32 v[18:19], v[68:69], v[36:37] op_sel_hi:[1,0] neg_lo:[0,1] neg_hi:[0,1]
	v_pk_add_f32 v[20:21], v[70:71], v[36:37] op_sel_hi:[1,0] neg_lo:[0,1] neg_hi:[0,1]
	v_pk_mul_f32 v[18:19], v[18:19], v[38:39] op_sel_hi:[1,0]
	v_pk_mul_f32 v[20:21], v[20:21], v[38:39] op_sel_hi:[1,0]
	v_pk_mul_f32 v[18:19], v[18:19], v[96:97]
	v_pk_mul_f32 v[20:21], v[20:21], v[98:99]
	v_pk_mul_f32 v[16:17], v[18:19], v[16:17]
	v_cvt_f32_f16_e32 v18, v121
	v_cvt_f32_f16_sdwa v19, v121 dst_sel:DWORD dst_unused:UNUSED_PAD src0_sel:WORD_1
	v_cvt_pk_bf16_f32 v16, v16, v17
	v_pk_mul_f32 v[18:19], v[20:21], v[18:19]
	s_nop 0
	v_cvt_pk_bf16_f32 v17, v18, v19
	global_store_dwordx2 v[26:27], v[16:17], off offset:576
	s_waitcnt vmcnt(7)
	v_cvt_f32_f16_e32 v16, v106
	v_cvt_f32_f16_sdwa v17, v106 dst_sel:DWORD dst_unused:UNUSED_PAD src0_sel:WORD_1
	v_pk_add_f32 v[18:19], v[64:65], v[36:37] op_sel_hi:[1,0] neg_lo:[0,1] neg_hi:[0,1]
	v_pk_add_f32 v[20:21], v[66:67], v[36:37] op_sel_hi:[1,0] neg_lo:[0,1] neg_hi:[0,1]
	v_pk_mul_f32 v[18:19], v[18:19], v[38:39] op_sel_hi:[1,0]
	v_pk_mul_f32 v[20:21], v[20:21], v[38:39] op_sel_hi:[1,0]
	v_pk_mul_f32 v[18:19], v[18:19], v[100:101]
	v_pk_mul_f32 v[20:21], v[20:21], v[102:103]
	v_pk_mul_f32 v[16:17], v[18:19], v[16:17]
	v_cvt_f32_f16_e32 v18, v107
	v_cvt_f32_f16_sdwa v19, v107 dst_sel:DWORD dst_unused:UNUSED_PAD src0_sel:WORD_1
	v_cvt_pk_bf16_f32 v16, v16, v17
	v_pk_mul_f32 v[18:19], v[20:21], v[18:19]
	s_nop 0
	v_cvt_pk_bf16_f32 v17, v18, v19
	global_store_dwordx2 v[26:27], v[16:17], off offset:608
	v_or_b32_e32 v16, 48, v140
	v_ashrrev_i32_e32 v17, 31, v16
	v_lshlrev_b64 v[68:69], 13, v[16:17]
	v_or_b32_e32 v68, s0, v68
	v_lshl_add_u64 v[16:17], s[36:37], 0, v[68:69]
	v_lshl_add_u64 v[70:71], v[16:17], 0, v[224:225]
	global_load_dwordx2 v[72:73], v[70:71], off
	global_load_dwordx4 v[20:23], v141, s[16:17]
	global_load_dwordx2 v[74:75], v[70:71], off offset:32
	global_load_dwordx4 v[24:27], v141, s[16:17] offset:64
	s_waitcnt lgkmcnt(0)
	v_mov_b32_e32 v16, v33
	v_mov_b32_e32 v17, v34
	v_mov_b32_e32 v33, v35
	v_pk_add_f32 v[16:17], v[16:17], v[32:33]
	global_load_dwordx2 v[76:77], v[70:71], off offset:64
	global_load_dwordx2 v[78:79], v[70:71], off offset:96
	global_load_dwordx2 v[80:81], v[70:71], off offset:512
	v_add_f32_e32 v16, v16, v17
	v_fmamk_f32 v16, v16, 0x3b000000, v245
	v_mul_f32_e32 v17, 0x4f800000, v16
	v_cmp_gt_f32_e32 vcc, s87, v16
	global_load_dwordx4 v[28:31], v141, s[16:17] offset:128
	global_load_dwordx4 v[32:35], v141, s[16:17] offset:192
	v_cndmask_b32_e32 v16, v16, v17, vcc
	v_sqrt_f32_e32 v17, v16
	v_lshl_add_u64 v[68:69], s[40:41], 0, v[68:69]
	v_add_u32_e32 v18, -1, v17
	v_fma_f32 v19, -v18, v17, v16
	v_cmp_ge_f32_e64 s[38:39], 0, v19
	v_add_u32_e32 v19, 1, v17
	s_waitcnt vmcnt(8)
	v_cvt_f32_f16_e32 v86, v72
	v_cndmask_b32_e64 v18, v17, v18, s[38:39]
	v_fma_f32 v17, -v19, v17, v16
	v_cmp_lt_f32_e64 s[38:39], 0, v17
	v_cvt_f32_f16_sdwa v87, v72 dst_sel:DWORD dst_unused:UNUSED_PAD src0_sel:WORD_1
	s_nop 0
	v_cndmask_b32_e64 v17, v18, v19, s[38:39]
	v_mul_f32_e32 v18, 0x37800000, v17
	v_cndmask_b32_e32 v17, v17, v18, vcc
	v_cmp_class_f32_e32 vcc, v16, v243
	s_nop 1
	v_cndmask_b32_e32 v17, v17, v16, vcc
	v_div_scale_f32 v18, s[2:3], v17, v17, 1.0
	v_rcp_f32_e32 v19, v18
	v_div_scale_f32 v40, vcc, 1.0, v17, 1.0
	v_mul_f32_e32 v16, 0x3b000000, v143
	v_fma_f32 v36, -v18, v19, 1.0
	v_fmac_f32_e32 v19, v36, v19
	global_load_dwordx4 v[36:39], v141, s[16:17] offset:1024
	v_mul_f32_e32 v41, v40, v19
	v_fma_f32 v42, -v18, v41, v40
	v_fmac_f32_e32 v41, v42, v19
	v_fma_f32 v18, -v18, v41, v40
	v_div_fmas_f32 v18, v18, v19, v41
	global_load_dwordx4 v[40:43], v141, s[16:17] offset:1088
	global_load_dwordx4 v[44:47], v141, s[16:17] offset:1152
	global_load_dwordx4 v[64:67], v141, s[16:17] offset:1216
	global_load_dwordx2 v[82:83], v[70:71], off offset:544
	global_load_dwordx2 v[84:85], v[70:71], off offset:576
	s_nop 0
	global_load_dwordx2 v[70:71], v[70:71], off offset:608
	v_div_fixup_f32 v18, v18, v17, 1.0
	v_pk_add_f32 v[8:9], v[8:9], v[16:17] op_sel_hi:[1,0] neg_lo:[0,1] neg_hi:[0,1]
	v_pk_add_f32 v[10:11], v[10:11], v[16:17] op_sel_hi:[1,0] neg_lo:[0,1] neg_hi:[0,1]
	v_pk_mul_f32 v[8:9], v[8:9], v[18:19] op_sel_hi:[1,0]
	v_pk_mul_f32 v[10:11], v[10:11], v[18:19] op_sel_hi:[1,0]
	s_waitcnt vmcnt(14)
	v_pk_mul_f32 v[8:9], v[8:9], v[20:21]
	v_cvt_f32_f16_e32 v20, v73
	v_cvt_f32_f16_sdwa v21, v73 dst_sel:DWORD dst_unused:UNUSED_PAD src0_sel:WORD_1
	v_pk_mul_f32 v[10:11], v[10:11], v[22:23]
	v_pk_mul_f32 v[8:9], v[8:9], v[86:87]
	v_pk_add_f32 v[0:1], v[0:1], v[16:17] op_sel_hi:[1,0] neg_lo:[0,1] neg_hi:[0,1]
	v_pk_mul_f32 v[10:11], v[10:11], v[20:21]
	v_cvt_pk_bf16_f32 v8, v8, v9
	v_cvt_pk_bf16_f32 v9, v10, v11
	v_lshl_add_u64 v[10:11], v[68:69], 0, v[224:225]
	global_store_dwordx2 v[10:11], v[8:9], off
	s_waitcnt vmcnt(14)
	v_cvt_f32_f16_e32 v8, v74
	v_cvt_f32_f16_sdwa v9, v74 dst_sel:DWORD dst_unused:UNUSED_PAD src0_sel:WORD_1
	v_pk_mul_f32 v[0:1], v[0:1], v[18:19] op_sel_hi:[1,0]
	v_pk_add_f32 v[2:3], v[2:3], v[16:17] op_sel_hi:[1,0] neg_lo:[0,1] neg_hi:[0,1]
	s_waitcnt vmcnt(13)
	v_pk_mul_f32 v[0:1], v[0:1], v[24:25]
	v_pk_mul_f32 v[2:3], v[2:3], v[18:19] op_sel_hi:[1,0]
	v_pk_mul_f32 v[0:1], v[0:1], v[8:9]
	v_cvt_f32_f16_e32 v8, v75
	v_cvt_f32_f16_sdwa v9, v75 dst_sel:DWORD dst_unused:UNUSED_PAD src0_sel:WORD_1
	v_pk_mul_f32 v[2:3], v[2:3], v[26:27]
	v_cvt_pk_bf16_f32 v0, v0, v1
	v_pk_mul_f32 v[2:3], v[2:3], v[8:9]
	s_nop 0
	v_cvt_pk_bf16_f32 v1, v2, v3
	global_store_dwordx2 v[10:11], v[0:1], off offset:32
	s_waitcnt vmcnt(13)
	v_cvt_f32_f16_e32 v0, v76
	v_cvt_f32_f16_sdwa v1, v76 dst_sel:DWORD dst_unused:UNUSED_PAD src0_sel:WORD_1
	v_pk_add_f32 v[2:3], v[4:5], v[16:17] op_sel_hi:[1,0] neg_lo:[0,1] neg_hi:[0,1]
	v_pk_add_f32 v[4:5], v[6:7], v[16:17] op_sel_hi:[1,0] neg_lo:[0,1] neg_hi:[0,1]
	v_pk_mul_f32 v[2:3], v[2:3], v[18:19] op_sel_hi:[1,0]
	v_pk_mul_f32 v[4:5], v[4:5], v[18:19] op_sel_hi:[1,0]
	s_waitcnt vmcnt(10)
	v_pk_mul_f32 v[2:3], v[2:3], v[28:29]
	v_pk_mul_f32 v[4:5], v[4:5], v[30:31]
	v_pk_mul_f32 v[0:1], v[2:3], v[0:1]
	v_cvt_f32_f16_e32 v2, v77
	v_cvt_f32_f16_sdwa v3, v77 dst_sel:DWORD dst_unused:UNUSED_PAD src0_sel:WORD_1
	v_cvt_pk_bf16_f32 v0, v0, v1
	v_pk_mul_f32 v[2:3], v[4:5], v[2:3]
	s_nop 0
	v_cvt_pk_bf16_f32 v1, v2, v3
	global_store_dwordx2 v[10:11], v[0:1], off offset:64
	v_cvt_f32_f16_e32 v0, v78
	v_cvt_f32_f16_sdwa v1, v78 dst_sel:DWORD dst_unused:UNUSED_PAD src0_sel:WORD_1
	v_pk_add_f32 v[2:3], v[12:13], v[16:17] op_sel_hi:[1,0] neg_lo:[0,1] neg_hi:[0,1]
	v_pk_add_f32 v[4:5], v[14:15], v[16:17] op_sel_hi:[1,0] neg_lo:[0,1] neg_hi:[0,1]
	v_pk_mul_f32 v[2:3], v[2:3], v[18:19] op_sel_hi:[1,0]
	v_pk_mul_f32 v[4:5], v[4:5], v[18:19] op_sel_hi:[1,0]
	s_waitcnt vmcnt(10)
	v_pk_mul_f32 v[2:3], v[2:3], v[32:33]
	v_pk_mul_f32 v[4:5], v[4:5], v[34:35]
	v_pk_mul_f32 v[0:1], v[2:3], v[0:1]
	v_cvt_f32_f16_e32 v2, v79
	v_cvt_f32_f16_sdwa v3, v79 dst_sel:DWORD dst_unused:UNUSED_PAD src0_sel:WORD_1
	v_cvt_pk_bf16_f32 v0, v0, v1
	v_pk_mul_f32 v[2:3], v[4:5], v[2:3]
	s_nop 0
	v_cvt_pk_bf16_f32 v1, v2, v3
	global_store_dwordx2 v[10:11], v[0:1], off offset:96
	v_cvt_f32_f16_e32 v0, v80
	v_cvt_f32_f16_sdwa v1, v80 dst_sel:DWORD dst_unused:UNUSED_PAD src0_sel:WORD_1
	v_pk_add_f32 v[2:3], v[60:61], v[16:17] op_sel_hi:[1,0] neg_lo:[0,1] neg_hi:[0,1]
	v_pk_add_f32 v[4:5], v[62:63], v[16:17] op_sel_hi:[1,0] neg_lo:[0,1] neg_hi:[0,1]
	v_pk_mul_f32 v[2:3], v[2:3], v[18:19] op_sel_hi:[1,0]
	v_pk_mul_f32 v[4:5], v[4:5], v[18:19] op_sel_hi:[1,0]
	s_waitcnt vmcnt(10)
	v_pk_mul_f32 v[2:3], v[2:3], v[36:37]
	s_nop 0
	v_pk_mul_f32 v[0:1], v[2:3], v[0:1]
	v_cvt_f32_f16_e32 v2, v81
	v_cvt_f32_f16_sdwa v3, v81 dst_sel:DWORD dst_unused:UNUSED_PAD src0_sel:WORD_1
	v_pk_mul_f32 v[4:5], v[4:5], v[38:39]
	v_cvt_pk_bf16_f32 v0, v0, v1
	v_pk_mul_f32 v[2:3], v[4:5], v[2:3]
	s_nop 0
	v_cvt_pk_bf16_f32 v1, v2, v3
	global_store_dwordx2 v[10:11], v[0:1], off offset:512
	s_waitcnt vmcnt(7)
	v_cvt_f32_f16_e32 v0, v82
	v_cvt_f32_f16_sdwa v1, v82 dst_sel:DWORD dst_unused:UNUSED_PAD src0_sel:WORD_1
	v_pk_add_f32 v[2:3], v[52:53], v[16:17] op_sel_hi:[1,0] neg_lo:[0,1] neg_hi:[0,1]
	v_pk_add_f32 v[4:5], v[54:55], v[16:17] op_sel_hi:[1,0] neg_lo:[0,1] neg_hi:[0,1]
	v_pk_mul_f32 v[2:3], v[2:3], v[18:19] op_sel_hi:[1,0]
	v_pk_mul_f32 v[4:5], v[4:5], v[18:19] op_sel_hi:[1,0]
	v_pk_mul_f32 v[2:3], v[2:3], v[40:41]
	v_pk_mul_f32 v[4:5], v[4:5], v[42:43]
	v_pk_mul_f32 v[0:1], v[2:3], v[0:1]
	v_cvt_f32_f16_e32 v2, v83
	v_cvt_f32_f16_sdwa v3, v83 dst_sel:DWORD dst_unused:UNUSED_PAD src0_sel:WORD_1
	v_cvt_pk_bf16_f32 v0, v0, v1
	v_pk_mul_f32 v[2:3], v[4:5], v[2:3]
	s_nop 0
	v_cvt_pk_bf16_f32 v1, v2, v3
	global_store_dwordx2 v[10:11], v[0:1], off offset:544
	s_waitcnt vmcnt(7)
	v_cvt_f32_f16_e32 v0, v84
	v_cvt_f32_f16_sdwa v1, v84 dst_sel:DWORD dst_unused:UNUSED_PAD src0_sel:WORD_1
	v_pk_add_f32 v[2:3], v[48:49], v[16:17] op_sel_hi:[1,0] neg_lo:[0,1] neg_hi:[0,1]
	v_pk_add_f32 v[4:5], v[50:51], v[16:17] op_sel_hi:[1,0] neg_lo:[0,1] neg_hi:[0,1]
	v_pk_mul_f32 v[2:3], v[2:3], v[18:19] op_sel_hi:[1,0]
	v_pk_mul_f32 v[4:5], v[4:5], v[18:19] op_sel_hi:[1,0]
	v_pk_mul_f32 v[2:3], v[2:3], v[44:45]
	v_pk_mul_f32 v[4:5], v[4:5], v[46:47]
	v_pk_mul_f32 v[0:1], v[2:3], v[0:1]
	v_cvt_f32_f16_e32 v2, v85
	v_cvt_f32_f16_sdwa v3, v85 dst_sel:DWORD dst_unused:UNUSED_PAD src0_sel:WORD_1
	v_cvt_pk_bf16_f32 v0, v0, v1
	v_pk_mul_f32 v[2:3], v[4:5], v[2:3]
	s_nop 0
	v_cvt_pk_bf16_f32 v1, v2, v3
	global_store_dwordx2 v[10:11], v[0:1], off offset:576
	s_waitcnt vmcnt(7)
	v_cvt_f32_f16_e32 v0, v70
	v_cvt_f32_f16_sdwa v1, v70 dst_sel:DWORD dst_unused:UNUSED_PAD src0_sel:WORD_1
	v_pk_add_f32 v[2:3], v[56:57], v[16:17] op_sel_hi:[1,0] neg_lo:[0,1] neg_hi:[0,1]
	v_pk_add_f32 v[4:5], v[58:59], v[16:17] op_sel_hi:[1,0] neg_lo:[0,1] neg_hi:[0,1]
	v_pk_mul_f32 v[2:3], v[2:3], v[18:19] op_sel_hi:[1,0]
	v_pk_mul_f32 v[4:5], v[4:5], v[18:19] op_sel_hi:[1,0]
	v_pk_mul_f32 v[2:3], v[2:3], v[64:65]
	v_pk_mul_f32 v[4:5], v[4:5], v[66:67]
	v_pk_mul_f32 v[0:1], v[2:3], v[0:1]
	v_cvt_f32_f16_e32 v2, v71
	v_cvt_f32_f16_sdwa v3, v71 dst_sel:DWORD dst_unused:UNUSED_PAD src0_sel:WORD_1
	v_cvt_pk_bf16_f32 v0, v0, v1
	v_pk_mul_f32 v[2:3], v[4:5], v[2:3]
	s_nop 0
	v_cvt_pk_bf16_f32 v1, v2, v3
	global_store_dwordx2 v[10:11], v[0:1], off offset:608
	s_cbranch_scc0 .LBB0_1817

.LBB0_1958:
	s_andn2_b64 vcc, exec, s[8:9]
	s_cbranch_vccnz .LBB0_2034
	s_mov_b32 s0, s80
	s_mov_b32 s2, -1
	s_mov_b64 s[8:9], s[96:97]
	v_mbcnt_lo_u32_b32 v0, s2, 0
	v_mbcnt_hi_u32_b32 v0, s2, v0
	s_add_i32 s2, s0, s67
	s_mov_b64 s[12:13], s[96:97]
	s_mov_b64 s[16:17], s[96:97]
	s_mov_b64 s[20:21], s[96:97]
	s_mov_b64 s[18:19], s[96:97]
	s_cmpk_gt_i32 s2, 0x7ff
	s_cbranch_scc1 .LBB0_1978
	s_load_dwordx2 s[20:21], s[20:21], 0x110
	s_nop 0
	s_load_dwordx2 s[8:9], s[8:9], 0x110
	s_nop 0
	s_load_dwordx2 s[22:23], s[12:13], 0x10
	s_nop 0
	s_load_dwordx2 s[16:17], s[16:17], 0x18
	s_nop 0
	s_load_dwordx2 s[18:19], s[18:19], 0x110
	s_waitcnt lgkmcnt(0)
	s_add_u32 s12, s20, 0x900000
	s_addc_u32 s13, s21, 0
	s_lshl_b32 s10, s48, 12
	s_lshl_b64 s[26:27], s[10:11], 2
	s_add_u32 s16, s16, s26
	s_addc_u32 s17, s17, s27
	s_add_u32 s22, s22, s26
	s_addc_u32 s23, s23, s27
	s_lshl_b32 s36, s2, 3
	v_lshlrev_b32_e32 v2, 3, v0
	s_cmp_lg_u64 s[20:21], 0
	v_ashrrev_i32_e32 v3, 31, v2
	s_cselect_b64 s[2:3], -1, 0
	v_cmp_eq_u32_e32 vcc, 0, v0
	v_lshlrev_b64 v[4:5], 2, v[2:3]
	s_and_b64 s[42:43], vcc, s[2:3]
	s_lshl_b32 s98, s80, 10
	v_lshl_add_u32 v194, v0, 4, s98
	global_load_dwordx4 v[196:199], v194, s[22:23]
	global_load_dwordx4 v[200:203], v194, s[16:17]
	v_lshlrev_b32_e32 v195, 5, v0
	s_waitcnt vmcnt(0)
	ds_write_b128 v194, v[196:199]
	ds_write_b128 v194, v[200:203] offset:8192
	s_waitcnt lgkmcnt(0)
	s_barrier
	v_lshl_add_u64 v[116:117], s[22:23], 0, v[4:5]
	v_lshl_add_u64 v[118:119], s[16:17], 0, v[4:5]
	s_mov_b64 s[2:3], 0x1000
	v_ashrrev_i32_e32 v1, 31, v0
	v_lshl_add_u64 v[120:121], v[116:117], 0, s[2:3]
	v_lshl_add_u64 v[122:123], v[118:119], 0, s[2:3]
	s_mov_b64 s[2:3], 0x1800
	s_lshl_b32 s0, s0, 4
	s_ashr_i32 s37, s36, 31
	v_lshl_add_u64 v[124:125], v[116:117], 0, s[2:3]
	v_lshl_add_u64 v[126:127], v[118:119], 0, s[2:3]
	s_add_i32 s44, s88, s0
	s_lshl_b64 s[46:47], s[36:37], 12
	v_lshl_add_u64 v[128:129], v[2:3], 1, s[18:19]
	v_lshl_add_u64 v[130:131], v[0:1], 4, s[8:9]
	s_branch .LBB0_1962

.LBB0_2307:
	s_andn2_b64 vcc, exec, s[8:9]
	s_cbranch_vccnz .LBB0_2383
	s_mov_b32 s0, s80
	s_mov_b32 s2, -1
	s_mov_b64 s[8:9], s[96:97]
	v_mbcnt_lo_u32_b32 v0, s2, 0
	v_mbcnt_hi_u32_b32 v0, s2, v0
	s_add_i32 s2, s0, s67
	s_mov_b64 s[12:13], s[96:97]
	s_mov_b64 s[16:17], s[96:97]
	s_mov_b64 s[20:21], s[96:97]
	s_mov_b64 s[18:19], s[96:97]
	s_cmpk_gt_i32 s2, 0x7ff
	s_cbranch_scc1 .LBB0_2327
	s_load_dwordx2 s[20:21], s[20:21], 0x110
	s_nop 0
	s_load_dwordx2 s[8:9], s[8:9], 0x110
	s_nop 0
	s_load_dwordx2 s[22:23], s[12:13], 0x10
	s_nop 0
	s_load_dwordx2 s[16:17], s[16:17], 0x18
	s_nop 0
	s_load_dwordx2 s[18:19], s[18:19], 0x110
	s_waitcnt lgkmcnt(0)
	s_add_u32 s12, s20, 0x920000
	s_addc_u32 s13, s21, 0
	s_lshl_b32 s3, s48, 12
	s_or_b32 s10, s3, 0x800
	s_lshl_b64 s[20:21], s[10:11], 2
	s_add_u32 s16, s16, s20
	s_addc_u32 s17, s17, s21
	v_lshlrev_b32_e32 v2, 3, v0
	s_add_u32 s20, s22, s20
	v_ashrrev_i32_e32 v3, 31, v2
	s_addc_u32 s21, s23, s21
	s_lshl_b32 s36, s2, 3
	v_lshlrev_b64 v[4:5], 2, v[2:3]
	s_mov_b64 s[2:3], 0x1000
	v_lshl_add_u64 v[6:7], v[4:5], 0, s[2:3]
	s_mov_b64 s[2:3], 0x1800
	v_ashrrev_i32_e32 v1, 31, v0
	s_lshl_b32 s98, s80, 10
	v_lshl_add_u32 v194, v0, 4, s98
	global_load_dwordx4 v[196:199], v194, s[20:21]
	global_load_dwordx4 v[200:203], v194, s[16:17]
	v_lshlrev_b32_e32 v195, 5, v0
	s_waitcnt vmcnt(0)
	ds_write_b128 v194, v[196:199]
	ds_write_b128 v194, v[200:203] offset:8192
	s_waitcnt lgkmcnt(0)
	s_barrier
	v_lshl_add_u64 v[116:117], s[20:21], 0, v[4:5]
	v_lshl_add_u64 v[118:119], s[16:17], 0, v[4:5]
	v_lshl_add_u64 v[4:5], v[4:5], 0, s[2:3]
	s_lshl_b32 s0, s0, 4
	s_ashr_i32 s37, s36, 31
	v_cmp_eq_u32_e64 s[40:41], 0, v0
	v_lshl_add_u64 v[120:121], s[20:21], 0, v[6:7]
	v_lshl_add_u64 v[122:123], s[16:17], 0, v[6:7]
	v_lshl_add_u64 v[124:125], s[20:21], 0, v[4:5]
	v_lshl_add_u64 v[126:127], s[16:17], 0, v[4:5]
	s_add_i32 s44, s88, s0
	s_lshl_b64 s[46:47], s[36:37], 12
	v_lshl_add_u64 v[128:129], v[2:3], 1, s[18:19]
	v_lshl_add_u64 v[130:131], v[0:1], 4, s[8:9]
	s_branch .LBB0_2311
